# same as v33 with all code after the prologue shifted by +32 bytes (instruction-fetch phase experiment)
# baseline (speedup 1.0000x reference)
; __global__ void __launch_bounds__(NTHR, 2) fwd_megakernel(Params p) {
;     ...
;     for (int rep = 0; rep < REP_LIGHT * REP_PRO; ++rep) { PHASE_IDS prologue(p, lds, gw, ngw, wave, lane); }
;     grid.sync();
.Lfold_done:
	s_nop 0
	s_nop 0
	s_nop 0
	s_nop 0
	s_nop 0
	s_nop 0
	s_nop 0
	s_nop 0
	s_nop 0
	s_nop 0
	s_nop 0
	s_nop 0
	s_nop 0
	s_nop 0
	s_nop 0
	s_nop 0
	s_nop 0
	s_nop 0
	s_nop 0
	s_nop 0
	s_nop 0
